# mixer: latent DFT as 128 half-tile units on 128 workgroups; key-norm bound of the odd head computed early by query block 8 of the even head so late-popped items skip the pre-pass
# baseline (speedup 1.0000x reference)
.LBB0_63:
	s_cmp_gt_i32 s71, 2
	s_mov_b64 s[2:3], -1
	s_cbranch_scc0 .LBB0_1082
	s_cmp_gt_i32 s71, 3
	s_cbranch_scc0 .LBB0_134
	s_mov_b64 s[2:3], s[0:1]
	s_load_dword s24, s[2:3], 0x98
	s_cmpk_gt_i32 s55, 0xbf
	s_movk_i32 s43, 0x120
	s_cbranch_scc1 .LBB0_74
	s_waitcnt lgkmcnt(0)
	s_bitcmp0_b32 s24, 6
	v_readlane_b32 s4, v254, 55
	s_cselect_b64 s[2:3], -1, 0
	v_readlane_b32 s5, v254, 56
	s_or_b64 s[2:3], s[4:5], s[2:3]
	s_andn2_b64 vcc, exec, s[2:3]
	s_cbranch_vccnz .LBB0_74
	s_waitcnt vmcnt(0)
	s_and_b32 s7, s55, 1
	s_add_i32 s7, s7, 1
	s_lshr_b32 s6, s55, 1
	s_add_i32 s2, s55, -64
	s_cmpk_lt_i32 s55, 0x80
	s_cselect_b32 s7, s7, 0
	s_cselect_b32 s6, s6, s2
	s_mov_b32 vcc_hi, s7
	v_mov_b32_e32 v15, v135
	s_bfe_u32 s58, s6, 0x10005
	v_lshlrev_b32_e32 v0, 4, v15
	v_add_u32_e32 v1, 0x2000, v0
	v_ashrrev_i32_e32 v2, 31, v1
	v_lshrrev_b32_e32 v2, 22, v2
	v_add_u32_e32 v2, v1, v2
	v_ashrrev_i32_e32 v2, 10, v2
	v_mul_i32_i24_e32 v3, 0x400, v2
	v_sub_u32_e32 v1, v1, v3
	v_lshrrev_b32_e32 v3, 4, v1
	v_bitop3_b32 v1, v3, v1, 32 bitop3:0x6c
	v_ashrrev_i32_e32 v3, 31, v1
	v_lshrrev_b32_e32 v3, 26, v3
	s_min_i32 s2, s6, 64
	v_add_u32_e32 v3, v1, v3
	s_and_b32 s3, s6, 31
	s_and_b32 s2, s2, 7
	s_bfe_u32 s8, s6, 0x20003
	s_lshl_b32 s9, s58, 22
	v_ashrrev_i32_e32 v4, 6, v3
	v_and_b32_e32 v3, 0xc0, v3
	s_cmp_lt_i32 s6, 64
	v_sub_u32_e32 v1, v1, v3
	s_cselect_b64 s[6:7], -1, 0
	v_ashrrev_i16_sdwa v1, v205, sext(v1) dst_sel:DWORD dst_unused:UNUSED_PAD src0_sel:DWORD src1_sel:BYTE_0
	s_and_b64 s[4:5], s[6:7], exec
	v_lshlrev_b32_e32 v5, 3, v2
	v_bfe_i32 v14, v1, 0, 16
	v_bfe_i32 v1, v15, 27, 1
	s_cselect_b32 s4, s8, s3
	s_mov_b32 s3, 0x5200000
	s_cselect_b32 s15, 11, 8
	v_and_b32_e32 v5, 0x7ffffff0, v5
	v_lshlrev_b32_e32 v2, 5, v2
	v_lshrrev_b32_e32 v1, 22, v1
	s_cselect_b32 s18, s3, 0x6200000
	s_mov_b32 s3, 0xeea4400
	s_movk_i32 s5, 0x100
	v_add_lshl_u32 v12, v4, v5, s15
	v_and_b32_e32 v13, 32, v2
	v_add_u32_e32 v1, v0, v1
	s_cselect_b32 s3, s3, 0xf6a4400
	s_cselect_b32 s19, 0x800, s5
	s_cselect_b32 s5, 23, 17
	s_cselect_b32 s8, 20, 17
	s_add_u32 s10, s80, s18
	v_or_b32_e32 v2, v12, v13
	v_and_b32_e32 v1, 0xfffffc00, v1
	s_addc_u32 s11, s81, 0
	s_lshl_b64 s[12:13], s[58:59], s5
	v_add_lshl_u32 v128, v2, v14, 1
	v_sub_u32_e32 v0, v0, v1
	v_ashrrev_i32_e32 v2, 31, v15
	s_add_u32 s10, s10, s12
	v_lshrrev_b32_e32 v1, 4, v0
	v_lshrrev_b32_e32 v2, 26, v2
	s_addc_u32 s11, s11, s13
	v_bitop3_b32 v1, v1, v0, 32 bitop3:0x6c
	v_ashrrev_i32_e32 v0, 31, v0
	v_add_u32_e32 v2, v15, v2
	s_add_u32 s3, s80, s3
	v_lshrrev_b32_e32 v0, 26, v0
	v_ashrrev_i32_e32 v2, 6, v2
	s_addc_u32 s5, s81, 0
	v_add_u32_e32 v0, v1, v0
	v_lshlrev_b32_e32 v3, 3, v2
	v_readfirstlane_b32 s14, v15
	s_add_u32 s27, s3, s9
	v_ashrrev_i32_e32 v0, 6, v0
	v_and_b32_e32 v3, 0x7ffffff0, v3
	s_addc_u32 s28, s5, 0
	s_ashr_i32 s22, s14, 6
	v_add_lshl_u32 v16, v0, v3, s15
	v_mul_i32_i24_e32 v0, 64, v0
	s_mov_b32 s3, s59
	s_mov_b32 s5, s59
	s_ashr_i32 s23, s14, 8
	s_lshl_b32 s25, s19, 8
	s_lshl_b32 s26, s22, 10
	v_lshlrev_b32_e32 v2, 5, v2
	v_sub_u32_e32 v0, v1, v0
	s_lshl_b64 s[16:17], s[2:3], s8
	s_lshr_b32 vcc_lo, vcc_hi, 1
	s_lshl_b32 vcc_lo, vcc_lo, 19
	s_add_u32 s16, s16, vcc_lo
	s_addc_u32 s17, s17, 0
	s_lshl_b64 s[8:9], s[4:5], s8
	v_and_b32_e32 v17, 32, v2
	v_ashrrev_i16_sdwa v0, v205, sext(v0) dst_sel:DWORD dst_unused:UNUSED_PAD src0_sel:DWORD src1_sel:BYTE_0
	s_add_u32 s8, s27, s8
	v_or_b32_e32 v2, v16, v17
	v_bfe_i32 v18, v0, 0, 16
	s_addc_u32 s9, s28, s9
	s_add_i32 s3, s26, 0
	v_add_lshl_u32 v132, v2, v18, 1
	s_add_i32 m0, s3, 0x10000
	v_mov_b32_e32 v129, v133
	global_load_lds_dwordx4 v132, s[8:9]
	s_add_i32 m0, s3, 0x12000
	s_add_u32 s10, s10, s16
	global_load_lds_dwordx4 v128, s[8:9]
	s_addc_u32 s11, s11, s17
	s_mov_b32 m0, s3
	s_add_i32 s5, s3, 0x2000
	global_load_lds_dwordx4 v132, s[10:11]
	s_mov_b32 m0, s5
	s_add_u32 s28, s8, s25
	global_load_lds_dwordx4 v128, s[10:11]
	s_addc_u32 s29, s9, 0
	s_add_i32 m0, s3, 0x14000
	v_lshl_add_u64 v[8:9], s[28:29], 0, v[132:133]
	global_load_lds_dwordx4 v132, s[28:29]
	s_add_i32 m0, s3, 0x16000
	s_add_u32 s30, s10, s25
	s_addc_u32 s31, s11, 0
	s_add_i32 s27, s3, 0x4000
	v_lshl_add_u64 v[10:11], s[28:29], 0, v[128:129]
	global_load_lds_dwordx4 v128, s[28:29]
	s_mov_b32 m0, s27
	s_add_i32 s28, s3, 0x6000
	global_load_lds_dwordx4 v132, s[30:31]
	s_mov_b32 m0, s28
	v_lshl_add_u64 v[0:1], s[8:9], 0, v[132:133]
	global_load_lds_dwordx4 v128, s[30:31]
	v_lshl_add_u64 v[2:3], s[8:9], 0, v[128:129]
	v_lshl_add_u64 v[4:5], s[10:11], 0, v[132:133]
	v_lshl_add_u64 v[6:7], s[10:11], 0, v[128:129]
	s_cmp_lg_u32 s23, 1
	s_cbranch_scc1 .LBB0_69
	s_barrier

.LBB0_70:
	s_add_i32 s35, s18, 2
	s_add_u32 s16, s12, 0x100
	s_addc_u32 s17, s13, 0
	s_cmp_lg_u32 s34, s18
	s_cselect_b32 s22, s16, 0
	s_cselect_b32 s23, s17, 0
	s_add_u32 s18, s10, s22
	s_addc_u32 s19, s11, s23
	s_add_i32 s36, 0, 0x10000
	s_add_u32 s22, s8, s22
	s_addc_u32 s23, s9, s23
	v_lshl_add_u64 v[190:191], v[130:131], 0, s[12:13]
	s_add_i32 m0, s3, 0xc000
	ds_read_b128 v[170:173], v153
	ds_read_b128 v[178:181], v153 offset:2048
	ds_read_b128 v[186:189], v153 offset:4096
	ds_read_b128 v[220:223], v153 offset:6144
	ds_read_b128 v[174:177], v153 offset:1024
	ds_read_b128 v[182:185], v153 offset:3072
	ds_read_b128 v[216:219], v153 offset:5120
	ds_read_b128 v[224:227], v153 offset:7168
	global_load_lds_dwordx4 v[190:191], off
	v_lshl_add_u64 v[190:191], v[150:151], 0, s[12:13]
	s_add_i32 m0, s3, 0xe000
	s_nop 0
	global_load_lds_dwordx4 v[190:191], off
	s_waitcnt lgkmcnt(8)
	s_waitcnt vmcnt(10)
	s_barrier
	s_waitcnt lgkmcnt(4)
	s_setprio 1
	v_mfma_f32_16x16x32_bf16 v[124:127], v[154:157], v[170:173], v[124:127]
	v_mfma_f32_16x16x32_bf16 v[120:123], v[162:165], v[170:173], v[120:123]
	v_mfma_f32_16x16x32_bf16 v[116:119], v[154:157], v[178:181], v[116:119]
	v_mfma_f32_16x16x32_bf16 v[108:111], v[162:165], v[178:181], v[108:111]
	v_mfma_f32_16x16x32_bf16 v[100:103], v[154:157], v[186:189], v[100:103]
	v_mfma_f32_16x16x32_bf16 v[92:95], v[162:165], v[186:189], v[92:95]
	v_mfma_f32_16x16x32_bf16 v[84:87], v[154:157], v[220:223], v[84:87]
	v_mfma_f32_16x16x32_bf16 v[76:79], v[162:165], v[220:223], v[76:79]
	s_waitcnt lgkmcnt(0)
	v_mfma_f32_16x16x32_bf16 v[124:127], v[158:161], v[174:177], v[124:127]
	v_mfma_f32_16x16x32_bf16 v[120:123], v[166:169], v[174:177], v[120:123]
	v_mfma_f32_16x16x32_bf16 v[116:119], v[158:161], v[182:185], v[116:119]
	v_mfma_f32_16x16x32_bf16 v[108:111], v[166:169], v[182:185], v[108:111]
	v_mfma_f32_16x16x32_bf16 v[100:103], v[158:161], v[216:219], v[100:103]
	v_mfma_f32_16x16x32_bf16 v[92:95], v[166:169], v[216:219], v[92:95]
	v_mfma_f32_16x16x32_bf16 v[84:87], v[158:161], v[224:227], v[84:87]
	v_mfma_f32_16x16x32_bf16 v[76:79], v[166:169], v[224:227], v[76:79]
	s_setprio 0
	s_barrier
	s_add_i32 s37, 0, 0x14000
	v_add_u32_e32 v190, s37, v152
	s_add_i32 s12, s36, s26
	ds_read_b128 v[228:231], v190
	ds_read_b128 v[236:239], v190 offset:2048
	ds_read_b128 v[232:235], v190 offset:1024
	ds_read_b128 v[240:243], v190 offset:3072
	v_lshl_add_u64 v[190:191], s[22:23], 0, v[132:133]
	s_mov_b32 m0, s12
	v_lshl_add_u64 v[244:245], s[22:23], 0, v[128:129]
	global_load_lds_dwordx4 v132, s[22:23]
	s_add_i32 m0, s12, 0x2000
	s_nop 0
	global_load_lds_dwordx4 v128, s[22:23]
	s_waitcnt vmcnt(10)
	s_barrier
	s_waitcnt lgkmcnt(2)
	s_setprio 1
	v_mfma_f32_16x16x32_bf16 v[112:115], v[228:231], v[170:173], v[112:115]
	v_mfma_f32_16x16x32_bf16 v[104:107], v[236:239], v[170:173], v[104:107]
	v_mfma_f32_16x16x32_bf16 v[96:99], v[228:231], v[178:181], v[96:99]
	v_mfma_f32_16x16x32_bf16 v[88:91], v[236:239], v[178:181], v[88:91]
	v_mfma_f32_16x16x32_bf16 v[80:83], v[228:231], v[186:189], v[80:83]
	v_mfma_f32_16x16x32_bf16 v[72:75], v[236:239], v[186:189], v[72:75]
	v_mfma_f32_16x16x32_bf16 v[68:71], v[228:231], v[220:223], v[68:71]
	v_mfma_f32_16x16x32_bf16 v[64:67], v[236:239], v[220:223], v[64:67]
	s_waitcnt lgkmcnt(0)
	v_mfma_f32_16x16x32_bf16 v[112:115], v[232:235], v[174:177], v[112:115]
	v_mfma_f32_16x16x32_bf16 v[104:107], v[240:243], v[174:177], v[104:107]
	v_mfma_f32_16x16x32_bf16 v[96:99], v[232:235], v[182:185], v[96:99]
	v_mfma_f32_16x16x32_bf16 v[88:91], v[240:243], v[182:185], v[88:91]
	v_mfma_f32_16x16x32_bf16 v[80:83], v[232:235], v[216:219], v[80:83]
	v_mfma_f32_16x16x32_bf16 v[72:75], v[240:243], v[216:219], v[72:75]
	v_mfma_f32_16x16x32_bf16 v[68:71], v[232:235], v[224:227], v[68:71]
	v_mfma_f32_16x16x32_bf16 v[64:67], v[240:243], v[224:227], v[64:67]
	s_setprio 0
	s_mov_b32 m0, s3
	s_barrier
	s_cmp_lg_u32 vcc_hi, 0
	s_cbranch_scc1 .Ldh_skr2
	ds_read_b128 v[170:173], v153 offset:16384
	ds_read_b128 v[178:181], v153 offset:18432
	ds_read_b128 v[186:189], v153 offset:20480
	ds_read_b128 v[220:223], v153 offset:22528
	ds_read_b128 v[174:177], v153 offset:17408
	ds_read_b128 v[182:185], v153 offset:19456
	ds_read_b128 v[216:219], v153 offset:21504
	ds_read_b128 v[224:227], v153 offset:23552
.Ldh_skr2:
	global_load_lds_dwordx4 v132, s[18:19]
	s_mov_b32 m0, s5
	s_nop 0
	global_load_lds_dwordx4 v128, s[18:19]
	s_waitcnt vmcnt(10)
	s_barrier
	s_waitcnt lgkmcnt(4)
	s_setprio 1
	s_cmp_lg_u32 vcc_hi, 0
	s_cbranch_scc1 .Ldh_skm2
	v_mfma_f32_16x16x32_bf16 v[60:63], v[154:157], v[170:173], v[60:63]
	v_mfma_f32_16x16x32_bf16 v[56:59], v[162:165], v[170:173], v[56:59]
	v_mfma_f32_16x16x32_bf16 v[52:55], v[154:157], v[178:181], v[52:55]
	v_mfma_f32_16x16x32_bf16 v[44:47], v[162:165], v[178:181], v[44:47]
	v_mfma_f32_16x16x32_bf16 v[36:39], v[154:157], v[186:189], v[36:39]
	v_mfma_f32_16x16x32_bf16 v[28:31], v[162:165], v[186:189], v[28:31]
	v_mfma_f32_16x16x32_bf16 v[20:23], v[154:157], v[220:223], v[20:23]
	v_mfma_f32_16x16x32_bf16 v[12:15], v[162:165], v[220:223], v[12:15]
	s_waitcnt lgkmcnt(0)
	v_mfma_f32_16x16x32_bf16 v[60:63], v[158:161], v[174:177], v[60:63]
	v_mfma_f32_16x16x32_bf16 v[56:59], v[166:169], v[174:177], v[56:59]
	v_mfma_f32_16x16x32_bf16 v[52:55], v[158:161], v[182:185], v[52:55]
	v_mfma_f32_16x16x32_bf16 v[44:47], v[166:169], v[182:185], v[44:47]
	v_mfma_f32_16x16x32_bf16 v[36:39], v[158:161], v[216:219], v[36:39]
	v_mfma_f32_16x16x32_bf16 v[28:31], v[166:169], v[216:219], v[28:31]
	v_mfma_f32_16x16x32_bf16 v[20:23], v[158:161], v[224:227], v[20:23]
	v_mfma_f32_16x16x32_bf16 v[12:15], v[166:169], v[224:227], v[12:15]
.Ldh_skm2:
	s_setprio 0
	s_barrier
	s_add_u32 s12, s22, s25
	s_addc_u32 s13, s23, 0
	s_add_i32 s22, s37, s26
	v_lshl_add_u64 v[250:251], s[12:13], 0, v[132:133]
	s_mov_b32 m0, s22
	v_lshl_add_u64 v[252:253], s[12:13], 0, v[128:129]
	global_load_lds_dwordx4 v132, s[12:13]
	s_add_i32 m0, s22, 0x2000
	s_nop 0
	global_load_lds_dwordx4 v128, s[12:13]
	v_add_u32_e32 v166, 0x18000, v152
	ds_read_b128 v[154:157], v166
	ds_read_b128 v[158:161], v166 offset:1024
	ds_read_b128 v[162:165], v166 offset:2048
	ds_read_b128 v[166:169], v166 offset:3072
	s_waitcnt vmcnt(10)
	s_barrier
	s_setprio 1
	s_cmp_lg_u32 vcc_hi, 0
	s_cbranch_scc1 .Ldh_skm3
	v_mfma_f32_16x16x32_bf16 v[48:51], v[228:231], v[170:173], v[48:51]
	v_mfma_f32_16x16x32_bf16 v[40:43], v[236:239], v[170:173], v[40:43]
	v_mfma_f32_16x16x32_bf16 v[32:35], v[228:231], v[178:181], v[32:35]
	v_mfma_f32_16x16x32_bf16 v[24:27], v[236:239], v[178:181], v[24:27]
	v_mfma_f32_16x16x32_bf16 v[16:19], v[228:231], v[186:189], v[16:19]
	v_mfma_f32_16x16x32_bf16 v[8:11], v[236:239], v[186:189], v[8:11]
	v_mfma_f32_16x16x32_bf16 v[4:7], v[228:231], v[220:223], v[4:7]
	v_mfma_f32_16x16x32_bf16 v[0:3], v[236:239], v[220:223], v[0:3]
	v_mfma_f32_16x16x32_bf16 v[48:51], v[232:235], v[174:177], v[48:51]
	v_mfma_f32_16x16x32_bf16 v[40:43], v[240:243], v[174:177], v[40:43]
	v_mfma_f32_16x16x32_bf16 v[32:35], v[232:235], v[182:185], v[32:35]
	v_mfma_f32_16x16x32_bf16 v[24:27], v[240:243], v[182:185], v[24:27]
	v_mfma_f32_16x16x32_bf16 v[16:19], v[232:235], v[216:219], v[16:19]
	v_mfma_f32_16x16x32_bf16 v[8:11], v[240:243], v[216:219], v[8:11]
	v_mfma_f32_16x16x32_bf16 v[4:7], v[232:235], v[224:227], v[4:7]
	v_mfma_f32_16x16x32_bf16 v[0:3], v[240:243], v[224:227], v[0:3]
.Ldh_skm3:
	s_setprio 0
	s_add_i32 s22, 0, 0x18000
	s_barrier
	s_add_u32 s12, s18, s25
	s_addc_u32 s13, s19, 0
	s_mov_b32 m0, s27
	ds_read_b128 v[170:173], v153 offset:32768
	ds_read_b128 v[178:181], v153 offset:34816
	ds_read_b128 v[186:189], v153 offset:36864
	ds_read_b128 v[220:223], v153 offset:38912
	ds_read_b128 v[174:177], v153 offset:33792
	ds_read_b128 v[182:185], v153 offset:35840
	ds_read_b128 v[216:219], v153 offset:37888
	ds_read_b128 v[224:227], v153 offset:39936
	global_load_lds_dwordx4 v132, s[12:13]
	s_mov_b32 m0, s28
	s_nop 0
	global_load_lds_dwordx4 v128, s[12:13]
	s_waitcnt lgkmcnt(8)
	s_waitcnt vmcnt(10)
	s_barrier
	s_waitcnt lgkmcnt(4)
	s_setprio 1
	v_mfma_f32_16x16x32_bf16 v[124:127], v[154:157], v[170:173], v[124:127]
	v_mfma_f32_16x16x32_bf16 v[120:123], v[162:165], v[170:173], v[120:123]
	v_mfma_f32_16x16x32_bf16 v[116:119], v[154:157], v[178:181], v[116:119]
	v_mfma_f32_16x16x32_bf16 v[108:111], v[162:165], v[178:181], v[108:111]
	v_mfma_f32_16x16x32_bf16 v[100:103], v[154:157], v[186:189], v[100:103]
	v_mfma_f32_16x16x32_bf16 v[92:95], v[162:165], v[186:189], v[92:95]
	v_mfma_f32_16x16x32_bf16 v[84:87], v[154:157], v[220:223], v[84:87]
	v_mfma_f32_16x16x32_bf16 v[76:79], v[162:165], v[220:223], v[76:79]
	s_waitcnt lgkmcnt(0)
	v_mfma_f32_16x16x32_bf16 v[124:127], v[158:161], v[174:177], v[124:127]
	v_mfma_f32_16x16x32_bf16 v[120:123], v[166:169], v[174:177], v[120:123]
	v_mfma_f32_16x16x32_bf16 v[116:119], v[158:161], v[182:185], v[116:119]
	v_mfma_f32_16x16x32_bf16 v[108:111], v[166:169], v[182:185], v[108:111]
	v_mfma_f32_16x16x32_bf16 v[100:103], v[158:161], v[216:219], v[100:103]
	v_mfma_f32_16x16x32_bf16 v[92:95], v[166:169], v[216:219], v[92:95]
	v_mfma_f32_16x16x32_bf16 v[84:87], v[158:161], v[224:227], v[84:87]
	v_mfma_f32_16x16x32_bf16 v[76:79], v[166:169], v[224:227], v[76:79]
	s_setprio 0
	s_barrier
	s_add_i32 s12, 0, 0x1c000
	s_add_i32 s13, s22, s26
	v_add_u32_e32 v200, s12, v152
	v_lshl_add_u64 v[190:191], v[190:191], 0, s[66:67]
	s_mov_b32 m0, s13
	ds_read_b128 v[228:231], v200
	ds_read_b128 v[236:239], v200 offset:2048
	ds_read_b128 v[232:235], v200 offset:1024
	ds_read_b128 v[240:243], v200 offset:3072
	global_load_lds_dwordx4 v[190:191], off
	v_lshl_add_u64 v[190:191], v[244:245], 0, s[66:67]
	s_add_i32 m0, s13, 0x2000
	s_nop 0
	global_load_lds_dwordx4 v[190:191], off
	s_waitcnt vmcnt(10)
	s_barrier
	s_waitcnt lgkmcnt(2)
	s_setprio 1
	v_mfma_f32_16x16x32_bf16 v[112:115], v[228:231], v[170:173], v[112:115]
	v_mfma_f32_16x16x32_bf16 v[104:107], v[236:239], v[170:173], v[104:107]
	v_mfma_f32_16x16x32_bf16 v[96:99], v[228:231], v[178:181], v[96:99]
	v_mfma_f32_16x16x32_bf16 v[88:91], v[236:239], v[178:181], v[88:91]
	v_mfma_f32_16x16x32_bf16 v[80:83], v[228:231], v[186:189], v[80:83]
	v_mfma_f32_16x16x32_bf16 v[72:75], v[236:239], v[186:189], v[72:75]
	v_mfma_f32_16x16x32_bf16 v[68:71], v[228:231], v[220:223], v[68:71]
	v_mfma_f32_16x16x32_bf16 v[64:67], v[236:239], v[220:223], v[64:67]
	s_waitcnt lgkmcnt(0)
	v_mfma_f32_16x16x32_bf16 v[112:115], v[232:235], v[174:177], v[112:115]
	v_mfma_f32_16x16x32_bf16 v[104:107], v[240:243], v[174:177], v[104:107]
	v_mfma_f32_16x16x32_bf16 v[96:99], v[232:235], v[182:185], v[96:99]
	v_mfma_f32_16x16x32_bf16 v[88:91], v[240:243], v[182:185], v[88:91]
	v_mfma_f32_16x16x32_bf16 v[80:83], v[232:235], v[216:219], v[80:83]
	v_mfma_f32_16x16x32_bf16 v[72:75], v[240:243], v[216:219], v[72:75]
	v_mfma_f32_16x16x32_bf16 v[68:71], v[232:235], v[224:227], v[68:71]
	v_mfma_f32_16x16x32_bf16 v[64:67], v[240:243], v[224:227], v[64:67]
	s_setprio 0
	s_mov_b32 m0, s30
	s_barrier
	s_cmp_lg_u32 vcc_hi, 0
	s_cbranch_scc1 .Ldh_skr6
	ds_read_b128 v[170:173], v153 offset:49152
	ds_read_b128 v[178:181], v153 offset:51200
	ds_read_b128 v[186:189], v153 offset:53248
	ds_read_b128 v[220:223], v153 offset:55296
	ds_read_b128 v[174:177], v153 offset:50176
	ds_read_b128 v[182:185], v153 offset:52224
	ds_read_b128 v[216:219], v153 offset:54272
	ds_read_b128 v[224:227], v153 offset:56320
.Ldh_skr6:
	s_add_u32 s98, s18, 0x80
	s_addc_u32 s99, s19, 0
	global_load_lds_dwordx4 v132, s[98:99]
	s_mov_b32 m0, s31
	s_nop 0
	global_load_lds_dwordx4 v128, s[98:99]
	s_waitcnt vmcnt(10)
	s_barrier
	s_waitcnt lgkmcnt(4)
	s_setprio 1
	s_cmp_lg_u32 vcc_hi, 0
	s_cbranch_scc1 .Ldh_skm6
	v_mfma_f32_16x16x32_bf16 v[60:63], v[154:157], v[170:173], v[60:63]
	v_mfma_f32_16x16x32_bf16 v[56:59], v[162:165], v[170:173], v[56:59]
	v_mfma_f32_16x16x32_bf16 v[52:55], v[154:157], v[178:181], v[52:55]
	v_mfma_f32_16x16x32_bf16 v[44:47], v[162:165], v[178:181], v[44:47]
	v_mfma_f32_16x16x32_bf16 v[36:39], v[154:157], v[186:189], v[36:39]
	v_mfma_f32_16x16x32_bf16 v[28:31], v[162:165], v[186:189], v[28:31]
	v_mfma_f32_16x16x32_bf16 v[20:23], v[154:157], v[220:223], v[20:23]
	v_mfma_f32_16x16x32_bf16 v[12:15], v[162:165], v[220:223], v[12:15]
	s_waitcnt lgkmcnt(0)
	v_mfma_f32_16x16x32_bf16 v[60:63], v[158:161], v[174:177], v[60:63]
	v_mfma_f32_16x16x32_bf16 v[56:59], v[166:169], v[174:177], v[56:59]
	v_mfma_f32_16x16x32_bf16 v[52:55], v[158:161], v[182:185], v[52:55]
	v_mfma_f32_16x16x32_bf16 v[44:47], v[166:169], v[182:185], v[44:47]
	v_mfma_f32_16x16x32_bf16 v[36:39], v[158:161], v[216:219], v[36:39]
	v_mfma_f32_16x16x32_bf16 v[28:31], v[166:169], v[216:219], v[28:31]
	v_mfma_f32_16x16x32_bf16 v[20:23], v[158:161], v[224:227], v[20:23]
	v_mfma_f32_16x16x32_bf16 v[12:15], v[166:169], v[224:227], v[12:15]
.Ldh_skm6:
	s_setprio 0
	s_barrier
	s_add_i32 s12, s12, s26
	v_lshl_add_u64 v[154:155], v[250:251], 0, s[66:67]
	s_mov_b32 m0, s12
	s_nop 0
	global_load_lds_dwordx4 v[154:155], off
	v_lshl_add_u64 v[154:155], v[252:253], 0, s[66:67]
	s_add_i32 m0, s12, 0x2000
	s_nop 0
	global_load_lds_dwordx4 v[154:155], off
	v_add_u32_e32 v166, 0x10000, v152
	ds_read_b128 v[154:157], v166
	ds_read_b128 v[158:161], v166 offset:1024
	ds_read_b128 v[162:165], v166 offset:2048
	ds_read_b128 v[166:169], v166 offset:3072
	s_waitcnt vmcnt(10)
	s_barrier
	s_setprio 1
	s_cmp_lg_u32 vcc_hi, 0
	s_cbranch_scc1 .Ldh_skm7
	v_mfma_f32_16x16x32_bf16 v[48:51], v[228:231], v[170:173], v[48:51]
	v_mfma_f32_16x16x32_bf16 v[40:43], v[236:239], v[170:173], v[40:43]
	v_mfma_f32_16x16x32_bf16 v[32:35], v[228:231], v[178:181], v[32:35]
	v_mfma_f32_16x16x32_bf16 v[24:27], v[236:239], v[178:181], v[24:27]
	v_mfma_f32_16x16x32_bf16 v[16:19], v[228:231], v[186:189], v[16:19]
	v_mfma_f32_16x16x32_bf16 v[8:11], v[236:239], v[186:189], v[8:11]
	v_mfma_f32_16x16x32_bf16 v[4:7], v[228:231], v[220:223], v[4:7]
	v_mfma_f32_16x16x32_bf16 v[0:3], v[236:239], v[220:223], v[0:3]
	v_mfma_f32_16x16x32_bf16 v[48:51], v[232:235], v[174:177], v[48:51]
	v_mfma_f32_16x16x32_bf16 v[40:43], v[240:243], v[174:177], v[40:43]
	v_mfma_f32_16x16x32_bf16 v[32:35], v[232:235], v[182:185], v[32:35]
	v_mfma_f32_16x16x32_bf16 v[24:27], v[240:243], v[182:185], v[24:27]
	v_mfma_f32_16x16x32_bf16 v[16:19], v[232:235], v[216:219], v[16:19]
	v_mfma_f32_16x16x32_bf16 v[8:11], v[240:243], v[216:219], v[8:11]
	v_mfma_f32_16x16x32_bf16 v[4:7], v[232:235], v[224:227], v[4:7]
	v_mfma_f32_16x16x32_bf16 v[0:3], v[240:243], v[224:227], v[0:3]
.Ldh_skm7:
	s_setprio 0
	s_cmp_ge_u32 s35, s29
	s_mov_b64 s[12:13], s[16:17]
	s_mov_b32 s18, s35
	s_barrier
	s_cbranch_scc0 .LBB0_70
	s_waitcnt lgkmcnt(0)
	s_and_b64 s[6:7], s[6:7], exec
	v_mov_b32_e32 v128, v135
	s_mov_b64 s[6:7], s[0:1]
	s_load_dwordx2 s[6:7], s[6:7], 0x88
	s_cselect_b32 s3, 0x2000, 0
	v_readfirstlane_b32 s5, v128
	v_lshrrev_b32_e32 v129, 2, v128
	v_cvt_pk_bf16_f32 v104, v104, v105
	s_waitcnt lgkmcnt(0)
	s_add_u32 s6, s6, 0xfea4400
	s_addc_u32 s7, s7, 0
	s_ashr_i32 s8, s5, 2
	s_andn2_b32 s8, s8, 63
	v_and_or_b32 v128, v128, 15, s8
	s_lshr_b32 s5, s5, 1
	v_lshl_add_u32 v150, s2, 8, v128
	s_lshr_b32 vcc_lo, vcc_hi, 1
	v_lshl_add_u32 v150, vcc_lo, 7, v150
	s_lshl_b32 s2, s4, s15
	s_and_b32 s5, s5, 0x60
	s_add_i32 s2, s2, s3
	v_and_or_b32 v132, v129, 12, s5
	v_add_u32_e32 v130, s2, v150
	v_mov_b64_e32 v[128:129], s[6:7]
	v_mad_i64_i32 v[130:131], s[4:5], v130, s96, v[128:129]
	s_lshl_b32 s58, s58, 9
	v_lshl_add_u64 v[130:131], v[130:131], 0, s[58:59]
	v_lshlrev_b32_e32 v132, 1, v132
	v_lshl_add_u64 v[130:131], v[130:131], 0, v[132:133]
	v_cvt_pk_bf16_f32 v105, v106, v107
	global_store_dwordx2 v[130:131], v[104:105], off offset:1824
	v_add3_u32 v104, s2, 16, v150
	v_mad_i64_i32 v[104:105], s[4:5], v104, s96, v[128:129]
	v_lshl_add_u64 v[104:105], v[104:105], 0, s[58:59]
	v_lshl_add_u64 v[104:105], v[104:105], 0, v[132:133]
	v_cvt_pk_bf16_f32 v88, v88, v89
	v_cvt_pk_bf16_f32 v89, v90, v91
	global_store_dwordx2 v[104:105], v[88:89], off offset:1824
	v_add3_u32 v88, s2, 32, v150
	v_mad_i64_i32 v[88:89], s[4:5], v88, s96, v[128:129]
	v_lshl_add_u64 v[88:89], v[88:89], 0, s[58:59]
	v_lshl_add_u64 v[88:89], v[88:89], 0, v[132:133]
	v_cvt_pk_bf16_f32 v72, v72, v73
	v_cvt_pk_bf16_f32 v73, v74, v75
	global_store_dwordx2 v[88:89], v[72:73], off offset:1824
	v_add3_u32 v72, s2, 48, v150
	v_mad_i64_i32 v[72:73], s[4:5], v72, s96, v[128:129]
	v_lshl_add_u64 v[72:73], v[72:73], 0, s[58:59]
	v_lshl_add_u64 v[72:73], v[72:73], 0, v[132:133]
	v_cvt_pk_bf16_f32 v64, v64, v65
	s_add_i32 s3, s2, 0x80
	v_cvt_pk_bf16_f32 v65, v66, v67
	global_store_dwordx2 v[72:73], v[64:65], off offset:1824
	v_add_u32_e32 v64, s3, v150
	v_mad_i64_i32 v[64:65], s[4:5], v64, s96, v[128:129]
	v_lshl_add_u64 v[64:65], v[64:65], 0, s[58:59]
	v_lshl_add_u64 v[64:65], v[64:65], 0, v[132:133]
	v_cvt_pk_bf16_f32 v40, v40, v41
	s_add_i32 s3, s2, 0x90
	v_cvt_pk_bf16_f32 v41, v42, v43
	s_cmp_lg_u32 vcc_hi, 0
	s_cbranch_scc1 .Ldh_st0
	global_store_dwordx2 v[64:65], v[40:41], off offset:1824
.Ldh_st0:
	v_add_u32_e32 v40, s3, v150
	v_mad_i64_i32 v[40:41], s[4:5], v40, s96, v[128:129]
	v_lshl_add_u64 v[40:41], v[40:41], 0, s[58:59]
	v_lshl_add_u64 v[40:41], v[40:41], 0, v[132:133]
	v_cvt_pk_bf16_f32 v24, v24, v25
	s_add_i32 s3, s2, 0xa0
	v_cvt_pk_bf16_f32 v25, v26, v27
	s_cmp_lg_u32 vcc_hi, 0
	s_cbranch_scc1 .Ldh_st1
	global_store_dwordx2 v[40:41], v[24:25], off offset:1824
.Ldh_st1:
	v_add_u32_e32 v24, s3, v150
	v_mad_i64_i32 v[24:25], s[4:5], v24, s96, v[128:129]
	v_lshl_add_u64 v[24:25], v[24:25], 0, s[58:59]
	v_lshl_add_u64 v[24:25], v[24:25], 0, v[132:133]
	v_cvt_pk_bf16_f32 v8, v8, v9
	s_addk_i32 s2, 0xb0
	v_cvt_pk_bf16_f32 v9, v10, v11
	s_cmp_lg_u32 vcc_hi, 0
	s_cbranch_scc1 .Ldh_st2
	global_store_dwordx2 v[24:25], v[8:9], off offset:1824
.Ldh_st2:
	v_add_u32_e32 v8, s2, v150
	v_mad_i64_i32 v[8:9], s[2:3], v8, s96, v[128:129]
	v_lshl_add_u64 v[8:9], v[8:9], 0, s[58:59]
	v_cvt_pk_bf16_f32 v106, v116, v117
	v_cvt_pk_bf16_f32 v107, v118, v119
	v_cvt_pk_bf16_f32 v90, v100, v101
	v_cvt_pk_bf16_f32 v91, v102, v103
	v_cvt_pk_bf16_f32 v74, v84, v85
	v_cvt_pk_bf16_f32 v75, v86, v87
	v_cvt_pk_bf16_f32 v42, v52, v53
	v_cvt_pk_bf16_f32 v43, v54, v55
	v_cvt_pk_bf16_f32 v26, v36, v37
	v_cvt_pk_bf16_f32 v27, v38, v39
	v_lshl_add_u64 v[8:9], v[8:9], 0, v[132:133]
	v_cvt_pk_bf16_f32 v10, v20, v21
	v_cvt_pk_bf16_f32 v11, v22, v23
	v_cvt_pk_bf16_f32 v124, v124, v125
	v_cvt_pk_bf16_f32 v125, v126, v127
	global_store_dwordx2 v[130:131], v[124:125], off offset:1536
	v_cvt_pk_bf16_f32 v120, v120, v121
	v_cvt_pk_bf16_f32 v121, v122, v123
	global_store_dwordx2 v[130:131], v[120:121], off offset:1568
	v_cvt_pk_bf16_f32 v112, v112, v113
	v_cvt_pk_bf16_f32 v113, v114, v115
	global_store_dwordx2 v[130:131], v[112:113], off offset:1792
	global_store_dwordx2 v[104:105], v[106:107], off offset:1536
	v_cvt_pk_bf16_f32 v106, v108, v109
	v_cvt_pk_bf16_f32 v107, v110, v111
	global_store_dwordx2 v[104:105], v[106:107], off offset:1568
	v_cvt_pk_bf16_f32 v96, v96, v97
	v_cvt_pk_bf16_f32 v97, v98, v99
	global_store_dwordx2 v[104:105], v[96:97], off offset:1792
	global_store_dwordx2 v[88:89], v[90:91], off offset:1536
	v_cvt_pk_bf16_f32 v90, v92, v93
	v_cvt_pk_bf16_f32 v91, v94, v95
	global_store_dwordx2 v[88:89], v[90:91], off offset:1568
	v_cvt_pk_bf16_f32 v80, v80, v81
	v_cvt_pk_bf16_f32 v81, v82, v83
	global_store_dwordx2 v[88:89], v[80:81], off offset:1792
	global_store_dwordx2 v[72:73], v[74:75], off offset:1536
	v_cvt_pk_bf16_f32 v74, v76, v77
	v_cvt_pk_bf16_f32 v75, v78, v79
	global_store_dwordx2 v[72:73], v[74:75], off offset:1568
	v_cvt_pk_bf16_f32 v68, v68, v69
	v_cvt_pk_bf16_f32 v69, v70, v71
	global_store_dwordx2 v[72:73], v[68:69], off offset:1792
	v_cvt_pk_bf16_f32 v60, v60, v61
	v_cvt_pk_bf16_f32 v61, v62, v63
	s_cmp_lg_u32 vcc_hi, 0
	s_cbranch_scc1 .Ldh_st3
	global_store_dwordx2 v[64:65], v[60:61], off offset:1536
.Ldh_st3:
	v_cvt_pk_bf16_f32 v56, v56, v57
	v_cvt_pk_bf16_f32 v57, v58, v59
	s_cmp_lg_u32 vcc_hi, 0
	s_cbranch_scc1 .Ldh_st4
	global_store_dwordx2 v[64:65], v[56:57], off offset:1568
.Ldh_st4:
	v_cvt_pk_bf16_f32 v48, v48, v49
	v_cvt_pk_bf16_f32 v49, v50, v51
	s_cmp_lg_u32 vcc_hi, 0
	s_cbranch_scc1 .Ldh_st5
	global_store_dwordx2 v[64:65], v[48:49], off offset:1792
.Ldh_st5:
	s_cmp_lg_u32 vcc_hi, 0
	s_cbranch_scc1 .Ldh_st6
	global_store_dwordx2 v[40:41], v[42:43], off offset:1536
.Ldh_st6:
	v_cvt_pk_bf16_f32 v42, v44, v45
	v_cvt_pk_bf16_f32 v43, v46, v47
	s_cmp_lg_u32 vcc_hi, 0
	s_cbranch_scc1 .Ldh_st7
	global_store_dwordx2 v[40:41], v[42:43], off offset:1568
.Ldh_st7:
	v_cvt_pk_bf16_f32 v32, v32, v33
	v_cvt_pk_bf16_f32 v33, v34, v35
	s_cmp_lg_u32 vcc_hi, 0
	s_cbranch_scc1 .Ldh_st8
	global_store_dwordx2 v[40:41], v[32:33], off offset:1792
.Ldh_st8:
	s_cmp_lg_u32 vcc_hi, 0
	s_cbranch_scc1 .Ldh_st9
	global_store_dwordx2 v[24:25], v[26:27], off offset:1536
.Ldh_st9:
	v_cvt_pk_bf16_f32 v26, v28, v29
	v_cvt_pk_bf16_f32 v27, v30, v31
	s_cmp_lg_u32 vcc_hi, 0
	s_cbranch_scc1 .Ldh_st10
	global_store_dwordx2 v[24:25], v[26:27], off offset:1568
.Ldh_st10:
	v_cvt_pk_bf16_f32 v16, v16, v17
	v_cvt_pk_bf16_f32 v17, v18, v19
	s_cmp_lg_u32 vcc_hi, 0
	s_cbranch_scc1 .Ldh_st11
	global_store_dwordx2 v[24:25], v[16:17], off offset:1792
.Ldh_st11:
	s_cmp_lg_u32 vcc_hi, 0
	s_cbranch_scc1 .Ldh_st12
	global_store_dwordx2 v[8:9], v[10:11], off offset:1536
.Ldh_st12:
	v_cvt_pk_bf16_f32 v10, v12, v13
	v_cvt_pk_bf16_f32 v11, v14, v15
	s_cmp_lg_u32 vcc_hi, 0
	s_cbranch_scc1 .Ldh_st13
	global_store_dwordx2 v[8:9], v[10:11], off offset:1568
.Ldh_st13:
	v_cvt_pk_bf16_f32 v4, v4, v5
	v_cvt_pk_bf16_f32 v5, v6, v7
	s_cmp_lg_u32 vcc_hi, 0
	s_cbranch_scc1 .Ldh_st14
	global_store_dwordx2 v[8:9], v[4:5], off offset:1792
.Ldh_st14:
	v_cvt_pk_bf16_f32 v0, v0, v1
	v_cvt_pk_bf16_f32 v1, v2, v3
	s_cmp_lg_u32 vcc_hi, 0
	s_cbranch_scc1 .Ldh_st15
	global_store_dwordx2 v[8:9], v[0:1], off offset:1824
.Ldh_st15:
	s_waitcnt vmcnt(0)
	s_cmpk_lt_u32 s14, 0x100
	s_cbranch_scc0 .LBB0_73
	s_barrier

.Lprio_done:
	v_and_b32_e32 v41, 15, v40
	v_lshl_or_b32 v0, v42, 4, v41
	s_add_i32 s24, s24, s25
	v_add_u32_e32 v104, s24, v0
	v_ashrrev_i32_e32 v105, 31, v104
	v_lshlrev_b64 v[0:1], 10, v[104:105]
	v_lshl_add_u64 v[0:1], s[4:5], 0, v[0:1]
	s_lshl_b32 s58, s35, 8
	v_lshl_add_u64 v[0:1], v[0:1], 0, s[58:59]
	v_and_b32_e32 v132, 48, v40
	v_lshl_add_u64 v[0:1], v[0:1], 0, v[132:133]
	s_mov_b64 s[4:5], 0xa2a4400
	v_lshl_add_u64 v[8:9], v[0:1], 0, s[4:5]
	s_mov_b32 s4, 0xa2a4000
	v_add_co_u32_e32 v10, vcc, s4, v0
	v_ashrrev_i32_e32 v36, 3, v40
	s_nop 0
	v_addc_co_u32_e32 v11, vcc, 0, v1, vcc
	global_load_dwordx4 v[0:3], v[8:9], off offset:64
	global_load_dwordx4 v[4:7], v[8:9], off offset:128
	global_load_dwordx4 v[12:15], v[10:11], off offset:1024
	s_nop 0
	global_load_dwordx4 v[8:11], v[8:9], off offset:192
	v_ashrrev_i32_e32 v37, 31, v36
	v_lshlrev_b64 v[34:35], 8, v[36:37]
	v_and_b32_e32 v37, 7, v40
	v_lshl_or_b32 v16, v37, 5, v34
	v_mov_b32_e32 v17, v35
	v_lshl_add_u64 v[32:33], s[18:19], 0, v[16:17]
	s_mov_b64 s[24:25], 0xc010
	v_and_b32_e32 v43, 63, v40
	v_bfe_u32 v105, v40, 4, 2
	s_lshl_b32 s22, s35, 7
	s_mov_b32 s4, 0
	s_lshr_b32 s23, s34, 6
	v_lshl_add_u64 v[38:39], v[32:33], 0, s[24:25]
	v_mov_b32_e32 v44, 0
	s_mov_b32 s99, 0
	s_cmpk_lt_i32 s37, 0x100
	s_cselect_b32 s5, 15, 1
	s_and_b32 s5, s5, s37
	s_cmpk_lt_i32 s37, 0x100
	s_cbranch_scc0 .Lkm_cls_ctx
	s_bitcmp1_b32 s37, 4
	s_cbranch_scc1 .Lkm_nondes
	s_cmp_eq_u32 s5, 0
	s_cbranch_scc1 .LBB0_117
	s_cmp_eq_u32 s5, 8
	s_cbranch_scc0 .Lkm_nondes
	s_mov_b32 s99, 1
	s_mov_b64 s[24:25], 0xa0000
	v_lshl_add_u64 v[38:39], v[38:39], 0, s[24:25]
	s_branch .LBB0_117
.Lkm_cls_ctx:
	s_cmp_eq_u32 s5, 0
	s_cbranch_scc1 .LBB0_117
.Lkm_nondes:
	s_lshr_b32 s24, s37, 4
	s_add_i32 s25, s37, 0xffffff00
	s_lshr_b32 s25, s25, 1
	s_add_i32 s25, s25, 16
	s_cmpk_lt_i32 s37, 0x100
	s_cselect_b32 s24, s24, s25
	s_mul_i32 s25, s40, 0x90
	s_add_i32 s24, s24, s25
	s_lshl_b32 s24, s24, 4
	s_add_u32 s24, s12, s24
	s_addc_u32 s25, s13, 0
	s_sub_u32 s24, s24, 0x9c02000
	s_subb_u32 s25, s25, 0

.Lkm_b3n:
	s_barrier
	v_max3_f32 v20, v19, v20, v21
	s_cmp_eq_u32 s99, 1
	s_cbranch_scc1 .Lkm_pub_do
	s_cmpk_lt_i32 s37, 0x100
	s_cselect_b32 s25, 15, 1
	s_and_b32 s25, s25, s37
	s_cmp_lg_u32 s25, 0
	s_cbranch_scc1 .Lkm_nopub
	s_cmpk_lt_i32 s37, 0x100
	s_cbranch_scc0 .Lkm_pub_do
	s_bitcmp1_b32 s37, 4
	s_cbranch_scc1 .Lkm_nopub
.Lkm_pub_do:
	s_lshr_b32 s4, s37, 4
	s_add_i32 s5, s37, 0xffffff00
	s_lshr_b32 s5, s5, 1
	s_add_i32 s5, s5, 16
	s_cmpk_lt_i32 s37, 0x100
	s_cselect_b32 s4, s4, s5
	s_mul_i32 s5, s40, 0x90
	s_add_i32 s4, s4, s5
	s_lshl_b32 s4, s4, 4
	s_add_u32 s4, s12, s4
	s_addc_u32 s5, s13, 0
	s_sub_u32 s4, s4, 0x9c02000
	s_subb_u32 s5, s5, 0
	s_lshl_b32 s25, s99, 4
	s_add_u32 s4, s4, s25
	s_addc_u32 s5, s5, 0
	v_cmp_eq_u32_e32 vcc, 0, v40
	s_and_b64 exec, exec, vcc
	v_mov_b32_e32 v46, v18
	v_mov_b32_e32 v47, v20
	global_store_dwordx2 v133, v[46:47], s[4:5] offset:8 sc1
	s_waitcnt vmcnt(0)
	v_mov_b32_e32 v45, 1
	global_store_dword v133, v45, s[4:5] sc1
	s_mov_b64 exec, -1
	s_cmp_eq_u32 s99, 1
	s_cbranch_scc0 .Lkm_nopub
	s_mov_b32 s99, 0
	s_lshr_b32 s24, s37, 4
	s_add_i32 s25, s37, 0xffffff00
	s_lshr_b32 s25, s25, 1
	s_add_i32 s25, s25, 16
	s_cmpk_lt_i32 s37, 0x100
	s_cselect_b32 s24, s24, s25
	s_mul_i32 s25, s40, 0x90
	s_add_i32 s24, s24, s25
	s_lshl_b32 s24, s24, 4
	s_add_u32 s24, s12, s24
	s_addc_u32 s25, s13, 0
	s_sub_u32 s24, s24, 0x9c02000
	s_subb_u32 s25, s25, 0
	s_branch .Lkm_spin
